# v6 plus retention gn-load batching and SGPR-base K/V prefetch addressing in the attention tile loop
# speedup vs baseline: 1.0210x; 1.0038x over previous
.LBB0_488:
	v_add_u32_e32 v138, 0x8800, v226
	v_cvt_pk_bf16_f32 v66, v2, v3
	v_cvt_pk_bf16_f32 v67, v4, v5
	v_cvt_pk_bf16_f32 v68, v6, v7
	v_cvt_pk_bf16_f32 v69, v8, v9
	ds_read2_b64 v[70:73], v138 offset1:2
	v_add_u32_e32 v139, 0xa800, v226
	s_waitcnt lgkmcnt(0)
	v_mfma_f32_32x32x16_bf16 v[82:97], v[70:73], v[66:69], 0
	ds_read2_b64 v[70:73], v139 offset0:64 offset1:66
	v_cvt_pk_bf16_f32 v130, v10, v11
	v_cvt_pk_bf16_f32 v131, v12, v13
	v_cvt_pk_bf16_f32 v132, v14, v15
	v_cvt_pk_bf16_f32 v133, v16, v17
	ds_read2_b64 v[134:137], v138 offset0:4 offset1:6
	s_waitcnt lgkmcnt(0)
	v_mfma_f32_32x32x16_bf16 v[82:97], v[134:137], v[130:133], v[82:97]
	ds_read2_b64 v[134:137], v139 offset0:68 offset1:70
	v_mfma_f32_32x32x16_bf16 v[66:81], v[70:73], v[66:69], 0
	s_waitcnt lgkmcnt(0)
	v_mfma_f32_32x32x16_bf16 v[66:81], v[134:137], v[130:133], v[66:81]
	v_cvt_pk_bf16_f32 v130, v18, v19
	v_cvt_pk_bf16_f32 v131, v20, v21
	v_cvt_pk_bf16_f32 v132, v22, v23
	v_cvt_pk_bf16_f32 v133, v24, v25
	ds_read2_b64 v[134:137], v138 offset0:8 offset1:10
	s_waitcnt lgkmcnt(0)
	v_mfma_f32_32x32x16_bf16 v[82:97], v[134:137], v[130:133], v[82:97]
	ds_read2_b64 v[134:137], v139 offset0:72 offset1:74
	s_waitcnt lgkmcnt(0)
	v_mfma_f32_32x32x16_bf16 v[66:81], v[134:137], v[130:133], v[66:81]
	v_cvt_pk_bf16_f32 v130, v26, v27
	v_cvt_pk_bf16_f32 v131, v28, v29
	v_cvt_pk_bf16_f32 v132, v30, v31
	v_cvt_pk_bf16_f32 v133, v32, v33
	ds_read2_b64 v[134:137], v138 offset0:12 offset1:14
	s_waitcnt lgkmcnt(0)
	v_mfma_f32_32x32x16_bf16 v[82:97], v[134:137], v[130:133], v[82:97]
	ds_read2_b64 v[134:137], v139 offset0:76 offset1:78
	s_waitcnt lgkmcnt(0)
	v_mfma_f32_32x32x16_bf16 v[66:81], v[134:137], v[130:133], v[66:81]
	v_cvt_pk_bf16_f32 v130, v34, v35
	v_cvt_pk_bf16_f32 v131, v36, v37
	v_cvt_pk_bf16_f32 v132, v38, v39
	v_cvt_pk_bf16_f32 v133, v40, v41
	ds_read2_b64 v[134:137], v138 offset0:16 offset1:18
	s_waitcnt lgkmcnt(0)
	v_mfma_f32_32x32x16_bf16 v[82:97], v[134:137], v[130:133], v[82:97]
	ds_read2_b64 v[134:137], v139 offset0:80 offset1:82
	s_waitcnt lgkmcnt(0)
	v_mfma_f32_32x32x16_bf16 v[66:81], v[134:137], v[130:133], v[66:81]
	v_cvt_pk_bf16_f32 v130, v42, v43
	v_cvt_pk_bf16_f32 v131, v44, v45
	v_cvt_pk_bf16_f32 v132, v46, v47
	v_cvt_pk_bf16_f32 v133, v48, v49
	ds_read2_b64 v[134:137], v138 offset0:20 offset1:22
	s_waitcnt lgkmcnt(0)
	v_mfma_f32_32x32x16_bf16 v[82:97], v[134:137], v[130:133], v[82:97]
	ds_read2_b64 v[134:137], v139 offset0:84 offset1:86
	s_waitcnt lgkmcnt(0)
	v_mfma_f32_32x32x16_bf16 v[66:81], v[134:137], v[130:133], v[66:81]
	v_cvt_pk_bf16_f32 v130, v50, v51
	v_cvt_pk_bf16_f32 v131, v52, v53
	v_cvt_pk_bf16_f32 v132, v54, v55
	v_cvt_pk_bf16_f32 v133, v56, v57
	ds_read2_b64 v[134:137], v138 offset0:24 offset1:26
	s_waitcnt lgkmcnt(0)
	v_mfma_f32_32x32x16_bf16 v[82:97], v[134:137], v[130:133], v[82:97]
	ds_read2_b64 v[134:137], v139 offset0:88 offset1:90
	s_waitcnt lgkmcnt(0)
	v_mfma_f32_32x32x16_bf16 v[66:81], v[134:137], v[130:133], v[66:81]
	v_cvt_pk_bf16_f32 v130, v58, v59
	v_cvt_pk_bf16_f32 v131, v60, v61
	v_cvt_pk_bf16_f32 v132, v62, v63
	v_cvt_pk_bf16_f32 v133, v64, v65
	ds_read2_b64 v[134:137], v138 offset0:28 offset1:30
	s_waitcnt lgkmcnt(0)
	v_mfma_f32_32x32x16_bf16 v[82:97], v[134:137], v[130:133], v[82:97]
	ds_read2_b64 v[134:137], v139 offset0:92 offset1:94
	s_waitcnt lgkmcnt(0)
	v_mfma_f32_32x32x16_bf16 v[66:81], v[134:137], v[130:133], v[66:81]
	s_waitcnt lgkmcnt(0)
	s_barrier
	ds_read_b128 v[130:133], v229
	ds_read_b64_tr_b16 v[142:143], v228
	ds_read_b64_tr_b16 v[144:145], v228 offset:2304
	s_waitcnt lgkmcnt(0)
	v_mfma_f32_32x32x16_bf16 v[82:97], v[130:133], v[142:145], v[82:97]
	ds_read_b128 v[130:133], v229 offset:4608
	s_waitcnt lgkmcnt(0)
	v_mfma_f32_32x32x16_bf16 v[66:81], v[130:133], v[142:145], v[66:81]
	ds_read_b128 v[130:133], v229 offset:32
	ds_read_b64_tr_b16 v[138:139], v228 offset:9216
	ds_read_b64_tr_b16 v[140:141], v228 offset:11520
	s_waitcnt lgkmcnt(0)
	v_mfma_f32_32x32x16_bf16 v[82:97], v[130:133], v[138:141], v[82:97]
	ds_read_b128 v[130:133], v229 offset:4640
	s_waitcnt lgkmcnt(0)
	v_mfma_f32_32x32x16_bf16 v[66:81], v[130:133], v[138:141], v[66:81]
	ds_read_b128 v[130:133], v229 offset:64
	ds_read_b64_tr_b16 v[134:135], v228 offset:18432
	ds_read_b64_tr_b16 v[136:137], v228 offset:20736
	s_waitcnt lgkmcnt(0)
	v_mfma_f32_32x32x16_bf16 v[82:97], v[130:133], v[134:137], v[82:97]
	ds_read_b128 v[130:133], v229 offset:4672
	s_waitcnt lgkmcnt(0)
	v_mfma_f32_32x32x16_bf16 v[66:81], v[130:133], v[134:137], v[66:81]
	ds_read_b128 v[242:245], v229 offset:96
	ds_read_b64_tr_b16 v[130:131], v228 offset:27648
	ds_read_b64_tr_b16 v[132:133], v228 offset:29952
	s_waitcnt lgkmcnt(0)
	v_mfma_f32_32x32x16_bf16 v[82:97], v[242:245], v[130:133], v[82:97]
	ds_read_b128 v[242:245], v229 offset:4704
	s_waitcnt lgkmcnt(0)
	v_mfma_f32_32x32x16_bf16 v[66:81], v[242:245], v[130:133], v[66:81]
	v_add_u32_e32 v233, v193, v223
	ds_read_b64_tr_b16 v[242:243], v233 offset:52224
	ds_read_b64_tr_b16 v[244:245], v233 offset:53504
	v_mul_f32_e64 v16, s56, v16
	v_mul_f32_e64 v17, s57, v17
	v_pk_mul_f32 v[14:15], s[44:45], v[14:15]
	v_pk_mul_f32 v[12:13], s[42:43], v[12:13]
	v_pk_mul_f32 v[10:11], s[40:41], v[10:11]
	v_pk_mul_f32 v[8:9], s[36:37], v[8:9]
	v_pk_mul_f32 v[6:7], s[18:19], v[6:7]
	v_pk_mul_f32 v[4:5], s[14:15], v[4:5]
	v_pk_mul_f32 v[2:3], s[10:11], v[2:3]
	v_pk_mul_f32 v[32:33], s[56:57], v[32:33]
	v_pk_mul_f32 v[30:31], s[44:45], v[30:31]
	s_waitcnt lgkmcnt(0)
	v_mfma_f32_32x32x16_bf16 v[2:17], v[242:245], v[142:145], v[2:17]
	ds_read_b64_tr_b16 v[242:243], v233 offset:57344
	ds_read_b64_tr_b16 v[244:245], v233 offset:58624
	v_mul_f32_e64 v28, s42, v28
	v_mul_f32_e64 v29, s43, v29
	v_mul_f32_e64 v26, s40, v26
	v_mul_f32_e64 v27, s41, v27
	v_pk_mul_f32 v[24:25], s[36:37], v[24:25]
	v_pk_mul_f32 v[22:23], s[18:19], v[22:23]
	v_pk_mul_f32 v[20:21], s[14:15], v[20:21]
	v_pk_mul_f32 v[18:19], s[10:11], v[18:19]
	s_waitcnt lgkmcnt(0)
	v_mfma_f32_32x32x16_bf16 v[2:17], v[242:245], v[138:141], v[2:17]
	ds_read_b64_tr_b16 v[242:243], v233 offset:62464
	ds_read_b64_tr_b16 v[244:245], v233 offset:63744
	v_mul_f32_e64 v48, s56, v48
	v_mul_f32_e64 v49, s57, v49
	v_mul_f32_e64 v46, s44, v46
	v_mul_f32_e64 v47, s45, v47
	v_pk_mul_f32 v[44:45], s[42:43], v[44:45]
	v_pk_mul_f32 v[42:43], s[40:41], v[42:43]
	v_pk_mul_f32 v[40:41], s[36:37], v[40:41]
	v_pk_mul_f32 v[38:39], s[18:19], v[38:39]
	s_waitcnt lgkmcnt(0)
	v_mfma_f32_32x32x16_bf16 v[2:17], v[242:245], v[134:137], v[2:17]
	ds_read_b64_tr_b16 v[242:243], v230 offset:62464
	ds_read_b64_tr_b16 v[244:245], v230 offset:63744
	v_mul_f32_e64 v36, s14, v36
	v_mul_f32_e64 v37, s15, v37
	v_mul_f32_e64 v34, s10, v34
	v_mul_f32_e64 v35, s11, v35
	v_pk_mul_f32 v[64:65], s[56:57], v[64:65]
	v_pk_mul_f32 v[62:63], s[44:45], v[62:63]
	v_pk_mul_f32 v[60:61], s[42:43], v[60:61]
	v_pk_mul_f32 v[58:59], s[40:41], v[58:59]
	s_waitcnt lgkmcnt(0)
	v_mfma_f32_32x32x16_bf16 v[2:17], v[242:245], v[130:133], v[2:17]
	ds_read_b64_tr_b16 v[242:243], v233 offset:52288
	ds_read_b64_tr_b16 v[244:245], v233 offset:53568
	v_mul_f32_e64 v56, s36, v56
	v_mul_f32_e64 v57, s37, v57
	v_mul_f32_e64 v54, s18, v54
	v_mul_f32_e64 v55, s19, v55
	v_pk_mul_f32 v[52:53], s[14:15], v[52:53]
	v_pk_mul_f32 v[50:51], s[10:11], v[50:51]
	s_waitcnt lgkmcnt(0)
	v_mfma_f32_32x32x16_bf16 v[18:33], v[242:245], v[142:145], v[18:33]
	ds_read_b64_tr_b16 v[242:243], v233 offset:57408
	ds_read_b64_tr_b16 v[244:245], v233 offset:58688
	s_waitcnt lgkmcnt(0)
	v_mfma_f32_32x32x16_bf16 v[18:33], v[242:245], v[138:141], v[18:33]
	ds_read_b64_tr_b16 v[242:243], v233 offset:62528
	ds_read_b64_tr_b16 v[244:245], v233 offset:63808
	s_waitcnt lgkmcnt(0)
	v_mfma_f32_32x32x16_bf16 v[18:33], v[242:245], v[134:137], v[18:33]
	ds_read_b64_tr_b16 v[242:243], v230 offset:62528
	ds_read_b64_tr_b16 v[244:245], v230 offset:63808
	s_waitcnt lgkmcnt(0)
	v_mfma_f32_32x32x16_bf16 v[18:33], v[242:245], v[130:133], v[18:33]
	ds_read_b64_tr_b16 v[242:243], v233 offset:52352
	ds_read_b64_tr_b16 v[244:245], v233 offset:53632
	s_waitcnt lgkmcnt(0)
	v_mfma_f32_32x32x16_bf16 v[34:49], v[242:245], v[142:145], v[34:49]
	ds_read_b64_tr_b16 v[242:243], v233 offset:57472
	ds_read_b64_tr_b16 v[244:245], v233 offset:58752
	s_waitcnt lgkmcnt(0)
	v_mfma_f32_32x32x16_bf16 v[34:49], v[242:245], v[138:141], v[34:49]
	ds_read_b64_tr_b16 v[242:243], v233 offset:62592
	ds_read_b64_tr_b16 v[244:245], v233 offset:63872
	s_waitcnt lgkmcnt(0)
	v_mfma_f32_32x32x16_bf16 v[34:49], v[242:245], v[134:137], v[34:49]
	ds_read_b64_tr_b16 v[242:243], v230 offset:62592
	ds_read_b64_tr_b16 v[244:245], v230 offset:63872
	s_waitcnt lgkmcnt(0)
	v_mfma_f32_32x32x16_bf16 v[34:49], v[242:245], v[130:133], v[34:49]
	ds_read_b64_tr_b16 v[242:243], v233 offset:52416
	ds_read_b64_tr_b16 v[244:245], v233 offset:53696
	s_waitcnt lgkmcnt(0)
	v_mfma_f32_32x32x16_bf16 v[50:65], v[242:245], v[142:145], v[50:65]
	ds_read_b64_tr_b16 v[142:143], v233 offset:57536
	ds_read_b64_tr_b16 v[144:145], v233 offset:58816
	s_waitcnt lgkmcnt(0)
	v_mfma_f32_32x32x16_bf16 v[50:65], v[142:145], v[138:141], v[50:65]
	ds_read_b64_tr_b16 v[138:139], v233 offset:62656
	ds_read_b64_tr_b16 v[140:141], v233 offset:63936
	s_waitcnt lgkmcnt(0)
	v_mfma_f32_32x32x16_bf16 v[50:65], v[138:141], v[134:137], v[50:65]
	ds_read_b64_tr_b16 v[134:135], v230 offset:62656
	ds_read_b64_tr_b16 v[136:137], v230 offset:63936
	s_waitcnt lgkmcnt(0)
	s_barrier
	ds_write_b32 v231, v82
	ds_write_b32 v231, v83 offset:1040
	ds_write_b32 v231, v84 offset:2080
	ds_write_b32 v231, v85 offset:3120
	ds_write_b32 v231, v86 offset:8320
	ds_write_b32 v231, v87 offset:9360
	ds_write_b32 v231, v88 offset:10400
	ds_write_b32 v231, v89 offset:11440
	ds_write_b32 v231, v90 offset:16640
	ds_write_b32 v231, v91 offset:17680
	ds_write_b32 v231, v92 offset:18720
	ds_write_b32 v231, v93 offset:19760
	ds_write_b32 v231, v94 offset:24960
	ds_write_b32 v231, v95 offset:26000
	ds_write_b32 v231, v96 offset:27040
	ds_write_b32 v231, v97 offset:28080
	ds_write_b32 v231, v66 offset:33280
	ds_write_b32 v231, v67 offset:34320
	ds_write_b32 v231, v68 offset:35360
	ds_write_b32 v231, v69 offset:36400
	ds_write_b32 v231, v70 offset:41600
	ds_write_b32 v231, v71 offset:42640
	ds_write_b32 v231, v72 offset:43680
	ds_write_b32 v231, v73 offset:44720
	ds_write_b32 v231, v74 offset:49920
	ds_write_b32 v231, v75 offset:50960
	ds_write_b32 v231, v76 offset:52000
	ds_write_b32 v231, v77 offset:53040
	ds_write_b32 v231, v78 offset:58240
	ds_write_b32 v231, v79 offset:59280
	ds_write_b32 v231, v80 offset:60320
	ds_write_b32 v231, v81 offset:61360
	s_waitcnt lgkmcnt(0)
	s_barrier
	ds_read_b128 v[94:97], v232
	ds_read_b128 v[90:93], v232 offset:128
	ds_read_b128 v[86:89], v232 offset:256
	ds_read_b128 v[82:85], v232 offset:384
	ds_read_b128 v[78:81], v232 offset:512
	ds_read_b128 v[74:77], v232 offset:640
	s_waitcnt lgkmcnt(5)
	v_mul_f32_e32 v66, v95, v95
	v_mul_f32_e32 v67, v97, v97
	v_fmac_f32_e32 v66, v94, v94
	v_fmac_f32_e32 v67, v96, v96
	v_add_f32_e32 v66, v66, v67
	s_waitcnt lgkmcnt(4)
	v_mul_f32_e32 v67, v91, v91
	v_mul_f32_e32 v68, v93, v93
	v_fmac_f32_e32 v67, v90, v90
	v_fmac_f32_e32 v68, v92, v92
	v_add_f32_e32 v67, v67, v68
	v_add_f32_e32 v66, v66, v67
	s_waitcnt lgkmcnt(3)
	v_mul_f32_e32 v67, v87, v87
	v_mul_f32_e32 v68, v89, v89
	v_fmac_f32_e32 v67, v86, v86
	v_fmac_f32_e32 v68, v88, v88
	v_add_f32_e32 v67, v67, v68
	v_add_f32_e32 v66, v66, v67
	s_waitcnt lgkmcnt(2)
	v_mul_f32_e32 v67, v83, v83
	v_mul_f32_e32 v68, v85, v85
	v_fmac_f32_e32 v67, v82, v82
	v_fmac_f32_e32 v68, v84, v84
	v_add_f32_e32 v67, v67, v68
	v_add_f32_e32 v66, v66, v67
	s_waitcnt lgkmcnt(1)
	v_mul_f32_e32 v67, v79, v79
	v_mul_f32_e32 v68, v81, v81
	v_fmac_f32_e32 v67, v78, v78
	v_fmac_f32_e32 v68, v80, v80
	ds_read_b128 v[70:73], v232 offset:768
	v_add_f32_e32 v67, v67, v68
	v_add_f32_e32 v66, v66, v67
	s_waitcnt lgkmcnt(1)
	v_mul_f32_e32 v67, v75, v75
	v_mul_f32_e32 v68, v77, v77
	v_fmac_f32_e32 v67, v74, v74
	v_fmac_f32_e32 v68, v76, v76
	v_add_f32_e32 v67, v67, v68
	v_add_f32_e32 v66, v66, v67
	s_waitcnt lgkmcnt(0)
	v_mul_f32_e32 v67, v71, v71
	v_mul_f32_e32 v68, v73, v73
	v_fmac_f32_e32 v67, v70, v70
	v_fmac_f32_e32 v68, v72, v72
	v_add_f32_e32 v67, v67, v68
	v_mfma_f32_32x32x16_bf16 v[50:65], v[134:137], v[130:133], v[50:65]
	v_add_f32_e32 v130, v66, v67
	ds_read_b128 v[66:69], v232 offset:896
	s_waitcnt vmcnt(7)
	v_and_b32_e32 v136, 0xffff0000, v178
	v_lshlrev_b32_e32 v137, 16, v179
	v_and_b32_e32 v138, 0xffff0000, v179
	s_waitcnt lgkmcnt(0)
	v_mul_f32_e32 v131, v67, v67
	v_mul_f32_e32 v132, v69, v69
	v_fmac_f32_e32 v131, v66, v66
	v_fmac_f32_e32 v132, v68, v68
	v_add_f32_e32 v131, v131, v132
	v_add_f32_e32 v130, v130, v131
	ds_bpermute_b32 v131, v194, v130
	s_waitcnt lgkmcnt(0)
	v_add_f32_e32 v130, v130, v131
	ds_bpermute_b32 v131, v195, v130
	s_waitcnt lgkmcnt(0)
	v_add_f32_e32 v130, v130, v131
	ds_bpermute_b32 v131, v196, v130
	s_waitcnt lgkmcnt(0)
	v_add_f32_e32 v130, v130, v131
	v_fmamk_f32 v130, v130, 0x3b800000, v207
	v_cmp_gt_f32_e32 vcc, s82, v130
	v_mul_f32_e32 v131, 0x4f800000, v130
	s_nop 0
	v_cndmask_b32_e32 v130, v130, v131, vcc
	v_sqrt_f32_e32 v131, v130
	s_nop 0
	v_add_u32_e32 v132, -1, v131
	v_fma_f32 v133, -v132, v131, v130
	v_cmp_ge_f32_e64 s[46:47], 0, v133
	v_add_u32_e32 v133, 1, v131
	s_nop 0
	v_cndmask_b32_e64 v132, v131, v132, s[46:47]
	v_fma_f32 v131, -v133, v131, v130
	v_cmp_lt_f32_e64 s[46:47], 0, v131
	s_nop 1
	v_cndmask_b32_e64 v131, v132, v133, s[46:47]
	v_mul_f32_e32 v132, 0x37800000, v131
	v_cndmask_b32_e32 v131, v131, v132, vcc
	v_cmp_class_f32_e32 vcc, v130, v227
	s_nop 1
	v_cndmask_b32_e32 v130, v131, v130, vcc
	v_div_scale_f32 v131, s[20:21], v130, v130, 1.0
	v_rcp_f32_e32 v132, v131
	s_nop 0
	v_fma_f32 v133, -v131, v132, 1.0
	v_fmac_f32_e32 v132, v133, v132
	v_div_scale_f32 v133, vcc, 1.0, v130, 1.0
	v_mul_f32_e32 v134, v133, v132
	v_fma_f32 v135, -v131, v134, v133
	v_fmac_f32_e32 v134, v135, v132
	v_fma_f32 v131, -v131, v134, v133
	v_div_fmas_f32 v131, v131, v132, v134
	v_div_fixup_f32 v134, v131, v130, 1.0
	global_load_dwordx4 v[130:133], v[146:147], off
	global_load_dwordx4 v[208:211], v[146:147], off offset:128
	global_load_dwordx4 v[212:215], v[146:147], off offset:256
	global_load_dwordx4 v[246:249], v[146:147], off offset:384
	v_lshlrev_b32_e32 v135, 16, v178
	v_mul_f32_e32 v94, v94, v134
	v_mul_f32_e32 v95, v95, v134
	v_mul_f32_e32 v90, v90, v134
	v_mul_f32_e32 v91, v91, v134
	v_mul_f32_e32 v86, v86, v134
	v_mul_f32_e32 v87, v87, v134
	v_mul_f32_e32 v82, v82, v134
	v_mul_f32_e32 v83, v83, v134
	v_mul_f32_e32 v78, v78, v134
	v_mul_f32_e32 v79, v79, v134
	v_mul_f32_e32 v74, v74, v134
	v_mul_f32_e32 v75, v75, v134
	v_mul_f32_e32 v70, v70, v134
	v_mul_f32_e32 v71, v71, v134
	v_mul_f32_e32 v66, v66, v134
	v_mul_f32_e32 v67, v67, v134
	s_andn2_b64 vcc, exec, s[76:77]
	s_waitcnt vmcnt(0)
	global_load_dwordx4 v[242:245], v[146:147], off offset:512
	global_load_dwordx4 v[140:143], v[146:147], off offset:640
	v_mul_f32_e32 v94, v130, v94
	v_mul_f32_e32 v130, 0xbfb8aa3b, v135
	v_exp_f32_e32 v130, v130
	v_mul_f32_e32 v94, v94, v135
	v_mul_f32_e32 v95, v131, v95
	v_mul_f32_e32 v95, v95, v136
	v_add_f32_e32 v130, 1.0, v130
	v_rcp_f32_e32 v130, v130
	v_and_b32_e32 v131, 0xffff0000, v176
	v_mul_f32_e32 v94, v130, v94
	v_mul_f32_e32 v130, 0xbfb8aa3b, v136
	v_exp_f32_e32 v130, v130
	s_nop 0
	v_add_f32_e32 v130, 1.0, v130
	v_rcp_f32_e32 v130, v130
	s_nop 0
	v_mul_f32_e32 v95, v130, v95
	v_cvt_pk_bf16_f32 v94, v94, v95
	v_mul_f32_e32 v95, v96, v134
	v_mul_f32_e32 v96, 0xbfb8aa3b, v137
	v_exp_f32_e32 v96, v96
	v_mul_f32_e32 v95, v132, v95
	v_mul_f32_e32 v95, v95, v137
	v_lshlrev_b32_e32 v130, 16, v176
	v_add_f32_e32 v96, 1.0, v96
	v_rcp_f32_e32 v96, v96
	v_lshlrev_b32_e32 v132, 16, v177
	v_mul_f32_e32 v95, v96, v95
	v_mul_f32_e32 v96, v97, v134
	v_mul_f32_e32 v97, 0xbfb8aa3b, v138
	v_exp_f32_e32 v97, v97
	v_mul_f32_e32 v96, v133, v96
	v_mul_f32_e32 v96, v96, v138
	v_and_b32_e32 v133, 0xffff0000, v177
	v_add_f32_e32 v97, 1.0, v97
	v_rcp_f32_e32 v97, v97
	s_nop 0
	v_mul_f32_e32 v96, v97, v96
	v_cvt_pk_bf16_f32 v95, v95, v96
	global_store_dwordx2 v[162:163], v[94:95], off offset:-256
	v_mul_f32_e32 v90, v208, v90
	v_mul_f32_e32 v94, 0xbfb8aa3b, v130
	v_exp_f32_e32 v94, v94
	v_mul_f32_e32 v90, v90, v130
	v_mul_f32_e32 v91, v209, v91
	v_mul_f32_e32 v91, v91, v131
	v_add_f32_e32 v94, 1.0, v94
	v_rcp_f32_e32 v94, v94
	v_and_b32_e32 v95, 0xffff0000, v174
	v_mul_f32_e32 v90, v94, v90
	v_mul_f32_e32 v94, 0xbfb8aa3b, v131
	v_exp_f32_e32 v94, v94
	s_nop 0
	v_add_f32_e32 v94, 1.0, v94
	v_rcp_f32_e32 v94, v94
	s_nop 0
	v_mul_f32_e32 v91, v94, v91
	v_cvt_pk_bf16_f32 v90, v90, v91
	v_mul_f32_e32 v91, v92, v134
	v_mul_f32_e32 v92, 0xbfb8aa3b, v132
	v_exp_f32_e32 v92, v92
	v_mul_f32_e32 v91, v210, v91
	v_mul_f32_e32 v91, v91, v132
	v_lshlrev_b32_e32 v94, 16, v174
	v_add_f32_e32 v92, 1.0, v92
	v_rcp_f32_e32 v92, v92
	v_lshlrev_b32_e32 v96, 16, v175
	v_mul_f32_e32 v91, v92, v91
	v_mul_f32_e32 v92, v93, v134
	v_mul_f32_e32 v93, 0xbfb8aa3b, v133
	v_exp_f32_e32 v93, v93
	v_mul_f32_e32 v92, v211, v92
	v_mul_f32_e32 v92, v92, v133
	v_and_b32_e32 v97, 0xffff0000, v175
	v_add_f32_e32 v93, 1.0, v93
	v_rcp_f32_e32 v93, v93
	s_nop 0
	v_mul_f32_e32 v92, v93, v92
	v_cvt_pk_bf16_f32 v91, v91, v92
	global_store_dwordx2 v[162:163], v[90:91], off offset:-192
	global_load_dwordx4 v[208:211], v[146:147], off offset:768
	v_mul_f32_e32 v86, v212, v86
	v_mul_f32_e32 v90, 0xbfb8aa3b, v94
	v_exp_f32_e32 v90, v90
	v_mul_f32_e32 v86, v86, v94
	v_mul_f32_e32 v87, v213, v87
	v_mul_f32_e32 v87, v87, v95
	v_add_f32_e32 v90, 1.0, v90
	v_rcp_f32_e32 v90, v90
	v_and_b32_e32 v91, 0xffff0000, v172
	v_mul_f32_e32 v86, v90, v86
	v_mul_f32_e32 v90, 0xbfb8aa3b, v95
	v_exp_f32_e32 v90, v90
	s_nop 0
	v_add_f32_e32 v90, 1.0, v90
	v_rcp_f32_e32 v90, v90
	s_nop 0
	v_mul_f32_e32 v87, v90, v87
	v_cvt_pk_bf16_f32 v86, v86, v87
	v_mul_f32_e32 v87, v88, v134
	v_mul_f32_e32 v88, 0xbfb8aa3b, v96
	v_exp_f32_e32 v88, v88
	v_mul_f32_e32 v87, v214, v87
	v_mul_f32_e32 v87, v87, v96
	v_lshlrev_b32_e32 v90, 16, v172
	v_add_f32_e32 v88, 1.0, v88
	v_rcp_f32_e32 v88, v88
	v_lshlrev_b32_e32 v92, 16, v173
	v_mul_f32_e32 v87, v88, v87
	v_mul_f32_e32 v88, v89, v134
	v_mul_f32_e32 v89, 0xbfb8aa3b, v97
	v_exp_f32_e32 v89, v89
	v_mul_f32_e32 v88, v215, v88
	v_mul_f32_e32 v88, v88, v97
	v_and_b32_e32 v93, 0xffff0000, v173
	v_add_f32_e32 v89, 1.0, v89
	v_rcp_f32_e32 v89, v89
	s_nop 0
	v_mul_f32_e32 v88, v89, v88
	v_cvt_pk_bf16_f32 v87, v87, v88
	global_store_dwordx2 v[162:163], v[86:87], off offset:-128
	global_load_dwordx4 v[212:215], v[146:147], off offset:896
	v_mul_f32_e32 v82, v82, v246
	v_mul_f32_e32 v86, 0xbfb8aa3b, v90
	v_exp_f32_e32 v86, v86
	v_mul_f32_e32 v82, v82, v90
	v_mul_f32_e32 v83, v83, v247
	v_mul_f32_e32 v83, v83, v91
	v_add_f32_e32 v86, 1.0, v86
	v_rcp_f32_e32 v86, v86
	v_and_b32_e32 v87, 0xffff0000, v170
	v_mul_f32_e32 v82, v86, v82
	v_mul_f32_e32 v86, 0xbfb8aa3b, v91
	v_exp_f32_e32 v86, v86
	s_nop 0
	v_add_f32_e32 v86, 1.0, v86
	v_rcp_f32_e32 v86, v86
	s_nop 0
	v_mul_f32_e32 v83, v86, v83
	v_cvt_pk_bf16_f32 v82, v82, v83
	v_mul_f32_e32 v83, v84, v134
	v_mul_f32_e32 v84, 0xbfb8aa3b, v92
	v_exp_f32_e32 v84, v84
	v_mul_f32_e32 v83, v83, v248
	v_mul_f32_e32 v83, v83, v92
	v_lshlrev_b32_e32 v86, 16, v170
	v_add_f32_e32 v84, 1.0, v84
	v_rcp_f32_e32 v84, v84
	v_lshlrev_b32_e32 v88, 16, v171
	v_mul_f32_e32 v83, v84, v83
	v_mul_f32_e32 v84, v85, v134
	v_mul_f32_e32 v85, 0xbfb8aa3b, v93
	v_exp_f32_e32 v85, v85
	v_mul_f32_e32 v84, v84, v249
	v_mul_f32_e32 v84, v84, v93
	v_and_b32_e32 v89, 0xffff0000, v171
	v_add_f32_e32 v85, 1.0, v85
	v_rcp_f32_e32 v85, v85
	s_nop 0
	v_mul_f32_e32 v84, v85, v84
	v_cvt_pk_bf16_f32 v83, v83, v84
	global_store_dwordx2 v[162:163], v[82:83], off offset:-64
	s_waitcnt vmcnt(7)
	v_mul_f32_e32 v78, v78, v242
	v_mul_f32_e32 v82, 0xbfb8aa3b, v86
	v_exp_f32_e32 v82, v82
	v_mul_f32_e32 v78, v78, v86
	v_mul_f32_e32 v79, v79, v243
	v_mul_f32_e32 v79, v79, v87
	v_add_f32_e32 v82, 1.0, v82
	v_rcp_f32_e32 v82, v82
	v_and_b32_e32 v83, 0xffff0000, v168
	v_mul_f32_e32 v78, v82, v78
	v_mul_f32_e32 v82, 0xbfb8aa3b, v87
	v_exp_f32_e32 v82, v82
	s_nop 0
	v_add_f32_e32 v82, 1.0, v82
	v_rcp_f32_e32 v82, v82
	s_nop 0
	v_mul_f32_e32 v79, v82, v79
	v_cvt_pk_bf16_f32 v78, v78, v79
	v_mul_f32_e32 v79, v80, v134
	v_mul_f32_e32 v80, 0xbfb8aa3b, v88
	v_exp_f32_e32 v80, v80
	v_mul_f32_e32 v79, v79, v244
	v_mul_f32_e32 v79, v79, v88
	v_lshlrev_b32_e32 v82, 16, v168
	v_add_f32_e32 v80, 1.0, v80
	v_rcp_f32_e32 v80, v80
	v_lshlrev_b32_e32 v84, 16, v169
	v_mul_f32_e32 v79, v80, v79
	v_mul_f32_e32 v80, v81, v134
	v_mul_f32_e32 v81, 0xbfb8aa3b, v89
	v_exp_f32_e32 v81, v81
	v_mul_f32_e32 v80, v80, v245
	v_mul_f32_e32 v80, v80, v89
	v_and_b32_e32 v85, 0xffff0000, v169
	v_add_f32_e32 v81, 1.0, v81
	v_rcp_f32_e32 v81, v81
	s_nop 0
	v_mul_f32_e32 v80, v81, v80
	v_cvt_pk_bf16_f32 v79, v79, v80
	global_store_dwordx2 v[162:163], v[78:79], off
	s_waitcnt vmcnt(7)
	v_mul_f32_e32 v74, v74, v140
	v_mul_f32_e32 v78, 0xbfb8aa3b, v82
	v_exp_f32_e32 v78, v78
	v_mul_f32_e32 v74, v74, v82
	v_mul_f32_e32 v75, v75, v141
	v_mul_f32_e32 v75, v75, v83
	v_add_f32_e32 v78, 1.0, v78
	v_rcp_f32_e32 v78, v78
	v_and_b32_e32 v79, 0xffff0000, v166
	v_mul_f32_e32 v74, v78, v74
	v_mul_f32_e32 v78, 0xbfb8aa3b, v83
	v_exp_f32_e32 v78, v78
	s_nop 0
	v_add_f32_e32 v78, 1.0, v78
	v_rcp_f32_e32 v78, v78
	s_nop 0
	v_mul_f32_e32 v75, v78, v75
	v_cvt_pk_bf16_f32 v74, v74, v75
	v_mul_f32_e32 v75, v76, v134
	v_mul_f32_e32 v76, 0xbfb8aa3b, v84
	v_exp_f32_e32 v76, v76
	v_mul_f32_e32 v75, v75, v142
	v_mul_f32_e32 v75, v75, v84
	v_lshlrev_b32_e32 v78, 16, v166
	v_add_f32_e32 v76, 1.0, v76
	v_rcp_f32_e32 v76, v76
	v_lshlrev_b32_e32 v80, 16, v167
	v_mul_f32_e32 v75, v76, v75
	v_mul_f32_e32 v76, v77, v134
	v_mul_f32_e32 v77, 0xbfb8aa3b, v85
	v_exp_f32_e32 v77, v77
	v_mul_f32_e32 v76, v76, v143
	v_mul_f32_e32 v76, v76, v85
	v_and_b32_e32 v81, 0xffff0000, v167
	v_add_f32_e32 v77, 1.0, v77
	v_rcp_f32_e32 v77, v77
	s_nop 0
	v_mul_f32_e32 v76, v77, v76
	v_cvt_pk_bf16_f32 v75, v75, v76
	global_store_dwordx2 v[162:163], v[74:75], off offset:64
	s_waitcnt vmcnt(5)
	v_mul_f32_e32 v70, v70, v208
	v_mul_f32_e32 v74, 0xbfb8aa3b, v78
	v_exp_f32_e32 v74, v74
	v_mul_f32_e32 v70, v70, v78
	v_mul_f32_e32 v71, v71, v209
	v_mul_f32_e32 v71, v71, v79
	v_add_f32_e32 v74, 1.0, v74
	v_rcp_f32_e32 v74, v74
	v_and_b32_e32 v75, 0xffff0000, v164
	v_mul_f32_e32 v70, v74, v70
	v_mul_f32_e32 v74, 0xbfb8aa3b, v79
	v_exp_f32_e32 v74, v74
	s_nop 0
	v_add_f32_e32 v74, 1.0, v74
	v_rcp_f32_e32 v74, v74
	s_nop 0
	v_mul_f32_e32 v71, v74, v71
	v_cvt_pk_bf16_f32 v70, v70, v71
	v_mul_f32_e32 v71, v72, v134
	v_mul_f32_e32 v72, 0xbfb8aa3b, v80
	v_exp_f32_e32 v72, v72
	v_mul_f32_e32 v71, v71, v210
	v_mul_f32_e32 v71, v71, v80
	v_lshlrev_b32_e32 v74, 16, v164
	v_add_f32_e32 v72, 1.0, v72
	v_rcp_f32_e32 v72, v72
	v_lshlrev_b32_e32 v76, 16, v165
	v_mul_f32_e32 v71, v72, v71
	v_mul_f32_e32 v72, v73, v134
	v_mul_f32_e32 v73, 0xbfb8aa3b, v81
	v_exp_f32_e32 v73, v73
	v_mul_f32_e32 v72, v72, v211
	v_mul_f32_e32 v72, v72, v81
	v_and_b32_e32 v77, 0xffff0000, v165
	v_add_f32_e32 v73, 1.0, v73
	v_rcp_f32_e32 v73, v73
	s_nop 0
	v_mul_f32_e32 v72, v73, v72
	v_cvt_pk_bf16_f32 v71, v71, v72
	global_store_dwordx2 v[162:163], v[70:71], off offset:128
	s_waitcnt vmcnt(4)
	v_mul_f32_e32 v66, v66, v212
	v_mul_f32_e32 v70, 0xbfb8aa3b, v74
	v_exp_f32_e32 v70, v70
	v_mul_f32_e32 v66, v66, v74
	v_mul_f32_e32 v67, v67, v213
	v_mul_f32_e32 v67, v67, v75
	v_add_f32_e32 v70, 1.0, v70
	v_rcp_f32_e32 v70, v70
	s_nop 0
	v_mul_f32_e32 v66, v70, v66
	v_mul_f32_e32 v70, 0xbfb8aa3b, v75
	v_exp_f32_e32 v70, v70
	s_nop 0
	v_add_f32_e32 v70, 1.0, v70
	v_rcp_f32_e32 v70, v70
	s_nop 0
	v_mul_f32_e32 v67, v70, v67
	v_cvt_pk_bf16_f32 v66, v66, v67
	v_mul_f32_e32 v67, v68, v134
	v_mul_f32_e32 v68, 0xbfb8aa3b, v76
	v_exp_f32_e32 v68, v68
	v_mul_f32_e32 v67, v67, v214
	v_mul_f32_e32 v67, v67, v76
	v_add_f32_e32 v68, 1.0, v68
	v_rcp_f32_e32 v68, v68
	s_nop 0
	v_mul_f32_e32 v67, v68, v67
	v_mul_f32_e32 v68, v69, v134
	v_mul_f32_e32 v69, 0xbfb8aa3b, v77
	v_exp_f32_e32 v69, v69
	v_mul_f32_e32 v68, v68, v215
	v_mul_f32_e32 v68, v68, v77
	v_add_f32_e32 v69, 1.0, v69
	v_rcp_f32_e32 v69, v69
	s_nop 0
	v_mul_f32_e32 v68, v69, v68
	v_cvt_pk_bf16_f32 v67, v67, v68
	global_store_dwordx2 v[162:163], v[66:67], off offset:192
	s_waitcnt lgkmcnt(0)
	s_barrier
	s_cbranch_vccnz .LBB0_483
	v_lshlrev_b32_e32 v66, 16, v98
	v_and_b32_e32 v67, 0xffff0000, v98
	v_mul_f32_e32 v66, v182, v66
	v_mul_f32_e32 v67, v182, v67
	ds_write_b128 v181, v[98:101]
	ds_write_b128 v181, v[102:105] offset:17408
	v_cvt_pk_bf16_f32 v66, v66, v67
	v_lshlrev_b32_e32 v67, 16, v99
	v_and_b32_e32 v68, 0xffff0000, v99
	v_mul_f32_e32 v67, v182, v67
	v_mul_f32_e32 v68, v182, v68
	v_cvt_pk_bf16_f32 v67, v67, v68
	v_lshlrev_b32_e32 v68, 16, v100
	v_and_b32_e32 v69, 0xffff0000, v100
	v_mul_f32_e32 v68, v182, v68
	v_mul_f32_e32 v69, v182, v69
	v_cvt_pk_bf16_f32 v68, v68, v69
	v_lshlrev_b32_e32 v69, 16, v101
	v_mul_f32_e32 v69, v182, v69
	v_and_b32_e32 v70, 0xffff0000, v101
	v_mul_f32_e32 v70, v182, v70
	v_cvt_pk_bf16_f32 v69, v69, v70
	ds_write_b128 v181, v[66:69] offset:34816
	v_lshlrev_b32_e32 v66, 16, v102
	v_and_b32_e32 v67, 0xffff0000, v102
	v_mul_f32_e32 v66, v183, v66
	v_mul_f32_e32 v67, v183, v67
	v_cvt_pk_bf16_f32 v66, v66, v67
	v_lshlrev_b32_e32 v67, 16, v103
	v_and_b32_e32 v68, 0xffff0000, v103
	v_mul_f32_e32 v67, v183, v67
	v_mul_f32_e32 v68, v183, v68
	v_cvt_pk_bf16_f32 v67, v67, v68
	v_lshlrev_b32_e32 v68, 16, v104
	v_and_b32_e32 v69, 0xffff0000, v104
	v_mul_f32_e32 v68, v183, v68
	v_mul_f32_e32 v69, v183, v69
	v_cvt_pk_bf16_f32 v68, v68, v69
	v_lshlrev_b32_e32 v69, 16, v105
	v_mul_f32_e32 v69, v183, v69
	v_and_b32_e32 v70, 0xffff0000, v105
	v_mul_f32_e32 v70, v183, v70
	v_cvt_pk_bf16_f32 v69, v69, v70
	ds_write_b128 v184, v[66:69] offset:52224
	ds_write_b128 v185, v[106:109]
	ds_write_b128 v185, v[110:113] offset:17408
	v_lshlrev_b32_e32 v66, 16, v106
	v_and_b32_e32 v67, 0xffff0000, v106
	v_mul_f32_e32 v66, v186, v66
	v_mul_f32_e32 v67, v186, v67
	v_cvt_pk_bf16_f32 v66, v66, v67
	v_lshlrev_b32_e32 v67, 16, v107
	v_and_b32_e32 v68, 0xffff0000, v107
	v_mul_f32_e32 v67, v186, v67
	v_mul_f32_e32 v68, v186, v68
	v_cvt_pk_bf16_f32 v67, v67, v68
	v_lshlrev_b32_e32 v68, 16, v108
	v_and_b32_e32 v69, 0xffff0000, v108
	v_mul_f32_e32 v68, v186, v68
	v_mul_f32_e32 v69, v186, v69
	v_cvt_pk_bf16_f32 v68, v68, v69
	v_lshlrev_b32_e32 v69, 16, v109
	v_mul_f32_e32 v69, v186, v69
	v_and_b32_e32 v70, 0xffff0000, v109
	v_mul_f32_e32 v70, v186, v70
	v_cvt_pk_bf16_f32 v69, v69, v70
	ds_write_b128 v185, v[66:69] offset:34816
	v_lshlrev_b32_e32 v66, 16, v110
	v_and_b32_e32 v67, 0xffff0000, v110
	v_mul_f32_e32 v66, v187, v66
	v_mul_f32_e32 v67, v187, v67
	v_cvt_pk_bf16_f32 v66, v66, v67
	v_lshlrev_b32_e32 v67, 16, v111
	v_and_b32_e32 v68, 0xffff0000, v111
	v_mul_f32_e32 v67, v187, v67
	v_mul_f32_e32 v68, v187, v68
	v_cvt_pk_bf16_f32 v67, v67, v68
	v_lshlrev_b32_e32 v68, 16, v112
	v_and_b32_e32 v69, 0xffff0000, v112
	v_mul_f32_e32 v68, v187, v68
	v_mul_f32_e32 v69, v187, v69
	v_cvt_pk_bf16_f32 v68, v68, v69
	v_lshlrev_b32_e32 v69, 16, v113
	v_mul_f32_e32 v69, v187, v69
	v_and_b32_e32 v70, 0xffff0000, v113
	v_mul_f32_e32 v70, v187, v70
	v_cvt_pk_bf16_f32 v69, v69, v70
	ds_write_b128 v188, v[66:69] offset:52224
	ds_write_b128 v189, v[114:117]
	ds_write_b128 v190, v[118:121]
	ds_write_b128 v191, v[122:125]
	ds_write_b128 v192, v[126:129]
	s_branch .LBB0_483

.Lattn_item_start:
	s_lshr_b32 s20, s22, 6
	s_sub_i32 s23, 7, s20
	s_andn2_b32 s20, 63, s22
	s_lshl_b32 s22, s20, 7
	s_lshl_b32 s70, s20, 1
	s_add_i32 s20, s23, 1
	v_cvt_f32_i32_e32 v0, s20
	s_mov_b32 s20, 0x42fc0000
	v_mov_b32_e32 v5, v206
	v_cmp_lt_f32_e32 vcc, s20, v0
	s_and_b64 s[20:21], vcc, exec
	s_cselect_b32 s20, 0xffffffc0, 0
	v_cndmask_b32_e32 v2, 0, v237, vcc
	v_sub_f32_e32 v0, v2, v0
	v_exp_f32_e32 v0, v0
	v_and_b32_e32 v4, 31, v5
	v_ashrrev_i32_e32 v6, 5, v5
	s_lshl_b32 s24, s13, 1
	v_ldexp_f32 v0, v0, s20
	s_or_b32 s20, s22, s45
	v_readfirstlane_b32 s48, v0
	v_or_b32_e32 v0, s20, v4
	s_lshl_b32 s20, s23, 7
	v_lshlrev_b32_e32 v0, 11, v0
	s_ashr_i32 s21, s20, 31
	v_lshl_add_u64 v[2:3], s[10:11], 0, v[0:1]
	s_lshl_b64 s[20:21], s[20:21], 1
	v_lshl_add_u64 v[216:217], v[2:3], 0, s[20:21]
	s_mov_b32 s25, s71
	v_lshlrev_b32_e32 v2, 3, v6
	v_mov_b32_e32 v0, 0x3fb8aa3b
	v_lshl_add_u64 v[8:9], v[216:217], 0, s[24:25]
	v_ashrrev_i32_e32 v3, 31, v2
	v_mul_f32_e32 v226, s48, v0
	v_lshl_add_u64 v[8:9], v[2:3], 1, v[8:9]
	v_div_scale_f32 v7, s[48:49], v226, v226, s86
	global_load_dwordx4 v[174:177], v[8:9], off
	global_load_dwordx4 v[178:181], v[8:9], off offset:32
	global_load_dwordx4 v[182:185], v[8:9], off offset:64
	global_load_dwordx4 v[186:189], v[8:9], off offset:96
	v_rcp_f32_e32 v8, v7
	s_sub_i32 s23, s22, 63
	v_cvt_f32_i32_e32 v0, s23
	s_or_b32 s22, s22, s44
	v_fma_f32 v9, -v7, v8, 1.0
	v_fmac_f32_e32 v8, v9, v8
	v_div_scale_f32 v9, vcc, s86, v226, s86
	v_mul_f32_e32 v10, v9, v8
	v_fma_f32 v11, -v7, v10, v9
	v_fmac_f32_e32 v10, v11, v8
	v_fma_f32 v7, -v7, v10, v9
	v_div_fmas_f32 v7, v7, v8, v10
	v_div_fixup_f32 v7, v7, v226, s86
	v_add_f32_e32 v0, v0, v7
	s_or_b32 s22, s22, 64
	v_add_u32_e32 v3, s3, v5
	v_mul_f32_e32 v0, 0x3c800000, v0
	s_add_u32 s48, s40, s20
	v_ceil_f32_e32 v0, v0
	s_addc_u32 s49, s41, s21
	v_ashrrev_i32_e32 v232, 4, v3
	v_cvt_i32_f32_e32 v7, v0
	s_mov_b32 s23, s71
	v_lshlrev_b32_e32 v0, 4, v5
	s_add_u32 s20, s42, s20
	v_ashrrev_i32_e32 v233, 31, v232
	v_and_b32_e32 v0, 0xf0, v0
	s_addc_u32 s21, s43, s21
	v_lshl_add_u64 v[8:9], v[232:233], 0, s[22:23]
	v_add_u32_e32 v3, 0x200, v3
	v_lshl_add_u64 v[228:229], s[48:49], 0, v[0:1]
	v_lshl_add_u64 v[230:231], s[20:21], 0, v[0:1]
	v_lshlrev_b64 v[8:9], 11, v[8:9]
	v_ashrrev_i32_e32 v234, 4, v3
	v_lshl_add_u64 v[10:11], v[228:229], 0, v[8:9]
	v_lshl_add_u64 v[8:9], v[230:231], 0, v[8:9]
	v_ashrrev_i32_e32 v235, 31, v234
	global_load_dwordx4 v[190:193], v[10:11], off
	global_load_dwordx4 v[194:197], v[8:9], off
	v_lshl_add_u64 v[8:9], v[234:235], 0, s[22:23]
	v_lshlrev_b64 v[8:9], 11, v[8:9]
	v_lshl_add_u64 v[10:11], v[228:229], 0, v[8:9]
	global_load_dwordx4 v[198:201], v[10:11], off
	v_lshl_add_u64 v[8:9], v[230:231], 0, v[8:9]
	global_load_dwordx4 v[202:205], v[8:9], off
	v_add_u32_e32 v221, 0, v0
	v_mul_lo_u32 v223, v232, s83
	v_add_u32_e32 v0, v221, v223
	v_mul_lo_u32 v225, v232, s84
	v_mul_lo_u32 v241, v234, s83
	v_mul_lo_u32 v242, v234, s84
	s_sub_u32 s101, s48, s40
	v_lshl_add_u32 v232, v232, 11, v221
	v_lshl_add_u32 v234, v234, 11, v221
	v_writelane_b32 v229, s101, 0
	v_readfirstlane_b32 s20, v7
	s_max_i32 s22, s20, 0
	s_sub_i32 s23, s70, s22
	s_add_i32 s23, s23, 2
	v_readfirstlane_b32 s25, v226
	s_mov_b64 s[20:21], -1
	s_cmp_gt_i32 s23, 0
	v_lshlrev_b32_e32 v243, 2, v5
	s_waitcnt vmcnt(3)
	ds_write_b128 v0, v[190:193]
	v_add_u32_e32 v0, v221, v225
	s_waitcnt vmcnt(2)
	ds_write_b128 v0, v[194:197] offset:17408
	v_add_u32_e32 v0, v221, v241
	s_waitcnt vmcnt(1)
	ds_write_b128 v0, v[198:201]
	v_add_u32_e32 v0, v221, v242
	s_waitcnt vmcnt(0)
	ds_write_b128 v0, v[202:205] offset:17408
	s_waitcnt lgkmcnt(0)
	s_barrier
	s_cbranch_scc1 .LBB0_503
	v_lshlrev_b32_e32 v80, 2, v5
	v_xor_b32_e32 v219, 0x80, v80
	s_mov_b64 s[20:21], 0

.LBB0_506:
	s_add_i32 s48, s70, 1
	s_cmp_gt_i32 s48, s22
	s_cselect_b64 s[20:21], -1, 0
	s_cmp_le_i32 s48, s22
	s_cbranch_scc1 .LBB0_509
	s_lshl_b64 s[50:51], s[70:71], 6
	s_add_u32 s50, s50, s44
	s_addc_u32 s51, s51, 0
	s_lshl_b64 s[50:51], s[50:51], 11
	v_readlane_b32 s101, v229, 0
	s_add_u32 s50, s50, s40
	s_addc_u32 s51, s51, s41
	s_add_u32 s50, s50, s101
	s_addc_u32 s51, s51, 0
	global_load_dwordx4 v[190:193], v232, s[50:51]
	global_load_dwordx4 v[198:201], v234, s[50:51]
	s_add_u32 s50, s50, 0x8000000
	s_addc_u32 s51, s51, 0
	global_load_dwordx4 v[194:197], v232, s[50:51]
	global_load_dwordx4 v[202:205], v234, s[50:51]
	s_cmp_gt_i32 s48, s24
	s_cbranch_scc0 .LBB0_510

.LBB0_516:
	s_andn2_b32 s20, 1, s25
	s_mul_i32 s20, s20, 0x9400
	v_add_u32_e32 v0, s20, v221
	v_add_u32_e32 v2, v0, v242
	v_add_u32_e32 v3, v0, v241
	v_add_u32_e32 v4, v0, v225
	v_add_u32_e32 v0, v0, v223
	s_waitcnt vmcnt(3)
	ds_write_b128 v0, v[190:193]
	s_waitcnt vmcnt(2)
	ds_write_b128 v3, v[198:201]
	s_waitcnt vmcnt(1)
	ds_write_b128 v4, v[194:197] offset:17408
	s_waitcnt vmcnt(0)
	ds_write_b128 v2, v[202:205] offset:17408
	s_branch .LBB0_505
